# final-output GEMM epilogue: one wait per half for the residual loads instead of vmcnt(0) before every store group
# baseline (speedup 1.0000x reference)
; __device__ __forceinline__ float bflo(unsigned u) { return __uint_as_float(u << 16); }
; __device__ __forceinline__ float bfhi(unsigned u) { return __uint_as_float(u & 0xffff0000u); }
;     __device__ __forceinline__ void operator()(const f32x4 (&acc)[2][2][4][2], const Unit& u, int wr, int wc, int fr, int fq) const {
;     ...
; #pragma unroll
;             for (int m = 0; m < 4; ++m)
; #pragma unroll
;                 for (int bj = 0; bj < 2; ++bj) o[m][bj] = *(const u32x4*)(X + (size_t)(row0 + ai * HALF + m * 16) * D + col0 + bj * HALF);
; #pragma unroll
;             for (int m = 0; m < 4; ++m) { const int r = row0 + ai * HALF + m * 16; float* dst = nullptr;
;                 if (r < MP) { const int b = r / TP, t = r - b * TP; if (t >= NMETA) dst = out + O_YP + ((size_t)b * SEQ + (t - NMETA)) * D; }
;                 else if (r < M) dst = out + O_YS + (size_t)(r - MP) * D;
;                 if (dst) {
; #pragma unroll
;                     for (int bj = 0; bj < 2; ++bj) { const u32x4 q = o[m][bj]; const f32x4 v0 = acc[ai][bj][m][0], v1 = acc[ai][bj][m][1];
;                         *(f32x4*)(dst + col0 + bj * HALF) = (f32x4){bflo(q.x) + v0[0], bfhi(q.x) + v0[1], bflo(q.y) + v0[2], bfhi(q.y) + v0[3]};
;                         *(f32x4*)(dst + col0 + bj * HALF + 4) = (f32x4){bflo(q.z) + v1[0], bfhi(q.z) + v1[1], bflo(q.w) + v1[2], bfhi(q.w) + v1[3]}; } } }
.LBB0_1165:
	s_or_b64 exec, exec, s[42:43]
	s_waitcnt vmcnt(0)
	v_cmp_ne_u64_e32 vcc, 0, v[186:187]
	s_mov_b64 s[42:43], exec
	s_and_b64 s[44:45], s[42:43], vcc
	v_mov_b64_e32 v[200:201], v[216:217]
	s_mov_b64 exec, s[44:45]
	s_cbranch_execz .LBB0_1167
	s_waitcnt vmcnt(0)
	v_lshlrev_b32_e32 v192, 16, v158
	v_and_b32_e32 v193, 0xffff0000, v158
	v_lshlrev_b32_e32 v158, 16, v159
	v_and_b32_e32 v159, 0xffff0000, v159
	v_lshl_add_u64 v[186:187], v[174:175], 2, v[186:187]
	v_pk_add_f32 v[126:127], v[126:127], v[192:193]
	v_pk_add_f32 v[128:129], v[128:129], v[158:159]
	global_store_dwordx4 v[186:187], v[126:129], off
	s_nop 1
	v_lshlrev_b32_e32 v126, 16, v160
	v_and_b32_e32 v127, 0xffff0000, v160
	v_pk_add_f32 v[122:123], v[122:123], v[126:127]
	v_lshlrev_b32_e32 v126, 16, v161
	v_and_b32_e32 v127, 0xffff0000, v161
	v_pk_add_f32 v[124:125], v[124:125], v[126:127]
	global_store_dwordx4 v[186:187], v[122:125], off offset:16
	s_nop 1
	v_lshlrev_b32_e32 v122, 16, v154
	v_and_b32_e32 v123, 0xffff0000, v154
	v_pk_add_f32 v[118:119], v[118:119], v[122:123]
	v_lshlrev_b32_e32 v122, 16, v155
	v_and_b32_e32 v123, 0xffff0000, v155
	v_pk_add_f32 v[120:121], v[120:121], v[122:123]
	global_store_dwordx4 v[186:187], v[118:121], off offset:512
	s_nop 1
	v_lshlrev_b32_e32 v118, 16, v156
	v_and_b32_e32 v119, 0xffff0000, v156
	v_pk_add_f32 v[114:115], v[114:115], v[118:119]
	v_lshlrev_b32_e32 v118, 16, v157
	v_and_b32_e32 v119, 0xffff0000, v157
	v_pk_add_f32 v[116:117], v[116:117], v[118:119]
	global_store_dwordx4 v[186:187], v[114:117], off offset:528

; __device__ __forceinline__ float bflo(unsigned u) { return __uint_as_float(u << 16); }
; __device__ __forceinline__ float bfhi(unsigned u) { return __uint_as_float(u & 0xffff0000u); }
;     __device__ __forceinline__ void operator()(const f32x4 (&acc)[2][2][4][2], const Unit& u, int wr, int wc, int fr, int fq) const {
;     ...
;             for (int m = 0; m < 4; ++m) { const int r = row0 + ai * HALF + m * 16; float* dst = nullptr;
;                 if (r < MP) { const int b = r / TP, t = r - b * TP; if (t >= NMETA) dst = out + O_YP + ((size_t)b * SEQ + (t - NMETA)) * D; }
;                 else if (r < M) dst = out + O_YS + (size_t)(r - MP) * D;
;                 if (dst) {
; #pragma unroll
;                     for (int bj = 0; bj < 2; ++bj) { const u32x4 q = o[m][bj]; const f32x4 v0 = acc[ai][bj][m][0], v1 = acc[ai][bj][m][1];
;                         *(f32x4*)(dst + col0 + bj * HALF) = (f32x4){bflo(q.x) + v0[0], bfhi(q.x) + v0[1], bflo(q.y) + v0[2], bfhi(q.y) + v0[3]};
;                         *(f32x4*)(dst + col0 + bj * HALF + 4) = (f32x4){bflo(q.z) + v1[0], bfhi(q.z) + v1[1], bflo(q.w) + v1[2], bfhi(q.w) + v1[3]}; } } }
.LBB0_1170:
	v_lshlrev_b32_e32 v116, 16, v150
	v_and_b32_e32 v117, 0xffff0000, v150
	v_pk_add_f32 v[110:111], v[110:111], v[116:117]
	v_lshlrev_b32_e32 v116, 16, v151
	v_and_b32_e32 v117, 0xffff0000, v151
	v_lshl_add_u64 v[114:115], v[174:175], 2, v[114:115]
	v_pk_add_f32 v[112:113], v[112:113], v[116:117]
	global_store_dwordx4 v[114:115], v[110:113], off
	s_nop 1
	v_lshlrev_b32_e32 v110, 16, v152
	v_and_b32_e32 v111, 0xffff0000, v152
	v_pk_add_f32 v[106:107], v[106:107], v[110:111]
	v_lshlrev_b32_e32 v110, 16, v153
	v_and_b32_e32 v111, 0xffff0000, v153
	v_pk_add_f32 v[108:109], v[108:109], v[110:111]
	global_store_dwordx4 v[114:115], v[106:109], off offset:16
	s_nop 1
	v_lshlrev_b32_e32 v106, 16, v146
	v_and_b32_e32 v107, 0xffff0000, v146
	v_pk_add_f32 v[102:103], v[102:103], v[106:107]
	v_lshlrev_b32_e32 v106, 16, v147
	v_and_b32_e32 v107, 0xffff0000, v147
	v_pk_add_f32 v[104:105], v[104:105], v[106:107]
	global_store_dwordx4 v[114:115], v[102:105], off offset:512
	s_nop 1
	v_lshlrev_b32_e32 v102, 16, v148
	v_and_b32_e32 v103, 0xffff0000, v148
	v_pk_add_f32 v[98:99], v[98:99], v[102:103]
	v_lshlrev_b32_e32 v102, 16, v149
	v_and_b32_e32 v103, 0xffff0000, v149
	v_pk_add_f32 v[100:101], v[100:101], v[102:103]
	global_store_dwordx4 v[114:115], v[98:101], off offset:528

; __device__ __forceinline__ float bflo(unsigned u) { return __uint_as_float(u << 16); }
; __device__ __forceinline__ float bfhi(unsigned u) { return __uint_as_float(u & 0xffff0000u); }
;     __device__ __forceinline__ void operator()(const f32x4 (&acc)[2][2][4][2], const Unit& u, int wr, int wc, int fr, int fq) const {
;     ...
;             for (int m = 0; m < 4; ++m) { const int r = row0 + ai * HALF + m * 16; float* dst = nullptr;
;                 if (r < MP) { const int b = r / TP, t = r - b * TP; if (t >= NMETA) dst = out + O_YP + ((size_t)b * SEQ + (t - NMETA)) * D; }
;                 else if (r < M) dst = out + O_YS + (size_t)(r - MP) * D;
;                 if (dst) {
; #pragma unroll
;                     for (int bj = 0; bj < 2; ++bj) { const u32x4 q = o[m][bj]; const f32x4 v0 = acc[ai][bj][m][0], v1 = acc[ai][bj][m][1];
;                         *(f32x4*)(dst + col0 + bj * HALF) = (f32x4){bflo(q.x) + v0[0], bfhi(q.x) + v0[1], bflo(q.y) + v0[2], bfhi(q.y) + v0[3]};
;                         *(f32x4*)(dst + col0 + bj * HALF + 4) = (f32x4){bflo(q.z) + v1[0], bfhi(q.z) + v1[1], bflo(q.w) + v1[2], bfhi(q.w) + v1[3]}; } } }
.LBB0_1174:
	v_lshlrev_b32_e32 v100, 16, v142
	v_and_b32_e32 v101, 0xffff0000, v142
	v_pk_add_f32 v[94:95], v[94:95], v[100:101]
	v_lshlrev_b32_e32 v100, 16, v143
	v_and_b32_e32 v101, 0xffff0000, v143
	v_lshl_add_u64 v[98:99], v[174:175], 2, v[98:99]
	v_pk_add_f32 v[96:97], v[96:97], v[100:101]
	global_store_dwordx4 v[98:99], v[94:97], off
	s_nop 1
	v_lshlrev_b32_e32 v94, 16, v144
	v_and_b32_e32 v95, 0xffff0000, v144
	v_pk_add_f32 v[90:91], v[90:91], v[94:95]
	v_lshlrev_b32_e32 v94, 16, v145
	v_and_b32_e32 v95, 0xffff0000, v145
	v_pk_add_f32 v[92:93], v[92:93], v[94:95]
	global_store_dwordx4 v[98:99], v[90:93], off offset:16
	s_nop 1
	v_lshlrev_b32_e32 v90, 16, v138
	v_and_b32_e32 v91, 0xffff0000, v138
	v_pk_add_f32 v[86:87], v[86:87], v[90:91]
	v_lshlrev_b32_e32 v90, 16, v139
	v_and_b32_e32 v91, 0xffff0000, v139
	v_pk_add_f32 v[88:89], v[88:89], v[90:91]
	global_store_dwordx4 v[98:99], v[86:89], off offset:512
	s_nop 1
	v_lshlrev_b32_e32 v86, 16, v140
	v_and_b32_e32 v87, 0xffff0000, v140
	v_pk_add_f32 v[82:83], v[82:83], v[86:87]
	v_lshlrev_b32_e32 v86, 16, v141
	v_and_b32_e32 v87, 0xffff0000, v141
	v_pk_add_f32 v[84:85], v[84:85], v[86:87]
	global_store_dwordx4 v[98:99], v[82:85], off offset:528

; __device__ __forceinline__ float bflo(unsigned u) { return __uint_as_float(u << 16); }
; __device__ __forceinline__ float bfhi(unsigned u) { return __uint_as_float(u & 0xffff0000u); }
;     __device__ __forceinline__ void operator()(const f32x4 (&acc)[2][2][4][2], const Unit& u, int wr, int wc, int fr, int fq) const {
;     ...
;             for (int m = 0; m < 4; ++m) { const int r = row0 + ai * HALF + m * 16; float* dst = nullptr;
;                 if (r < MP) { const int b = r / TP, t = r - b * TP; if (t >= NMETA) dst = out + O_YP + ((size_t)b * SEQ + (t - NMETA)) * D; }
;                 else if (r < M) dst = out + O_YS + (size_t)(r - MP) * D;
;                 if (dst) {
; #pragma unroll
;                     for (int bj = 0; bj < 2; ++bj) { const u32x4 q = o[m][bj]; const f32x4 v0 = acc[ai][bj][m][0], v1 = acc[ai][bj][m][1];
;                         *(f32x4*)(dst + col0 + bj * HALF) = (f32x4){bflo(q.x) + v0[0], bfhi(q.x) + v0[1], bflo(q.y) + v0[2], bfhi(q.y) + v0[3]};
;                         *(f32x4*)(dst + col0 + bj * HALF + 4) = (f32x4){bflo(q.z) + v1[0], bfhi(q.z) + v1[1], bflo(q.w) + v1[2], bfhi(q.w) + v1[3]}; } } }
.LBB0_1178:
	v_lshlrev_b32_e32 v84, 16, v134
	v_and_b32_e32 v85, 0xffff0000, v134
	v_pk_add_f32 v[78:79], v[78:79], v[84:85]
	v_lshlrev_b32_e32 v84, 16, v135
	v_and_b32_e32 v85, 0xffff0000, v135
	v_lshl_add_u64 v[82:83], v[174:175], 2, v[82:83]
	v_pk_add_f32 v[80:81], v[80:81], v[84:85]
	global_store_dwordx4 v[82:83], v[78:81], off
	s_nop 1
	v_lshlrev_b32_e32 v78, 16, v136
	v_and_b32_e32 v79, 0xffff0000, v136
	v_pk_add_f32 v[74:75], v[74:75], v[78:79]
	v_lshlrev_b32_e32 v78, 16, v137
	v_and_b32_e32 v79, 0xffff0000, v137
	v_pk_add_f32 v[76:77], v[76:77], v[78:79]
	global_store_dwordx4 v[82:83], v[74:77], off offset:16
	s_nop 1
	v_lshlrev_b32_e32 v74, 16, v130
	v_and_b32_e32 v75, 0xffff0000, v130
	v_pk_add_f32 v[70:71], v[70:71], v[74:75]
	v_lshlrev_b32_e32 v74, 16, v131
	v_and_b32_e32 v75, 0xffff0000, v131
	v_pk_add_f32 v[72:73], v[72:73], v[74:75]
	global_store_dwordx4 v[82:83], v[70:73], off offset:512
	s_nop 1
	v_lshlrev_b32_e32 v70, 16, v132
	v_and_b32_e32 v71, 0xffff0000, v132
	v_pk_add_f32 v[66:67], v[66:67], v[70:71]
	v_lshlrev_b32_e32 v70, 16, v133
	v_and_b32_e32 v71, 0xffff0000, v133
	v_pk_add_f32 v[68:69], v[68:69], v[70:71]
	global_store_dwordx4 v[82:83], v[66:69], off offset:528

;     __device__ __forceinline__ void operator()(const f32x4 (&acc)[2][2][4][2], const Unit& u, int wr, int wc, int fr, int fq) const {
;     ...
; #pragma unroll
;             for (int m = 0; m < 4; ++m)
; #pragma unroll
;                 for (int bj = 0; bj < 2; ++bj) o[m][bj] = *(const u32x4*)(X + (size_t)(row0 + ai * HALF + m * 16) * D + col0 + bj * HALF);
; #pragma unroll
;             for (int m = 0; m < 4; ++m) { const int r = row0 + ai * HALF + m * 16; float* dst = nullptr;
;                 if (r < MP) { const int b = r / TP, t = r - b * TP; if (t >= NMETA) dst = out + O_YP + ((size_t)b * SEQ + (t - NMETA)) * D; }
;                 else if (r < M) dst = out + O_YS + (size_t)(r - MP) * D;
.LBB0_1181:
	s_or_b64 exec, exec, s[42:43]
	s_waitcnt vmcnt(0)
	v_cmp_ne_u64_e32 vcc, 0, v[106:107]
	s_and_saveexec_b64 s[42:43], vcc
	s_cbranch_execz .LBB0_1183

; __device__ __forceinline__ float bflo(unsigned u) { return __uint_as_float(u << 16); }
; __device__ __forceinline__ float bfhi(unsigned u) { return __uint_as_float(u & 0xffff0000u); }
;     __device__ __forceinline__ void operator()(const f32x4 (&acc)[2][2][4][2], const Unit& u, int wr, int wc, int fr, int fq) const {
;     ...
;             for (int m = 0; m < 4; ++m) { const int r = row0 + ai * HALF + m * 16; float* dst = nullptr;
;                 if (r < MP) { const int b = r / TP, t = r - b * TP; if (t >= NMETA) dst = out + O_YP + ((size_t)b * SEQ + (t - NMETA)) * D; }
;                 else if (r < M) dst = out + O_YS + (size_t)(r - MP) * D;
;                 if (dst) {
; #pragma unroll
;                     for (int bj = 0; bj < 2; ++bj) { const u32x4 q = o[m][bj]; const f32x4 v0 = acc[ai][bj][m][0], v1 = acc[ai][bj][m][1];
;                         *(f32x4*)(dst + col0 + bj * HALF) = (f32x4){bflo(q.x) + v0[0], bfhi(q.x) + v0[1], bflo(q.y) + v0[2], bfhi(q.y) + v0[3]};
;                         *(f32x4*)(dst + col0 + bj * HALF + 4) = (f32x4){bflo(q.z) + v1[0], bfhi(q.z) + v1[1], bflo(q.w) + v1[2], bfhi(q.w) + v1[3]}; } } }
.LBB0_1186:
	v_lshlrev_b32_e32 v52, 16, v86
	v_and_b32_e32 v53, 0xffff0000, v86
	v_pk_add_f32 v[46:47], v[46:47], v[52:53]
	v_lshlrev_b32_e32 v52, 16, v87
	v_and_b32_e32 v53, 0xffff0000, v87
	v_lshl_add_u64 v[50:51], v[174:175], 2, v[50:51]
	v_pk_add_f32 v[48:49], v[48:49], v[52:53]
	global_store_dwordx4 v[50:51], v[46:49], off
	s_nop 1
	v_lshlrev_b32_e32 v46, 16, v88
	v_and_b32_e32 v47, 0xffff0000, v88
	v_pk_add_f32 v[42:43], v[42:43], v[46:47]
	v_lshlrev_b32_e32 v46, 16, v89
	v_and_b32_e32 v47, 0xffff0000, v89
	v_pk_add_f32 v[44:45], v[44:45], v[46:47]
	global_store_dwordx4 v[50:51], v[42:45], off offset:16
	s_nop 1
	v_lshlrev_b32_e32 v42, 16, v82
	v_and_b32_e32 v43, 0xffff0000, v82
	v_pk_add_f32 v[38:39], v[38:39], v[42:43]
	v_lshlrev_b32_e32 v42, 16, v83
	v_and_b32_e32 v43, 0xffff0000, v83
	v_pk_add_f32 v[40:41], v[40:41], v[42:43]
	global_store_dwordx4 v[50:51], v[38:41], off offset:512
	s_nop 1
	v_lshlrev_b32_e32 v38, 16, v84
	v_and_b32_e32 v39, 0xffff0000, v84
	v_pk_add_f32 v[34:35], v[34:35], v[38:39]
	v_lshlrev_b32_e32 v38, 16, v85
	v_and_b32_e32 v39, 0xffff0000, v85
	v_pk_add_f32 v[36:37], v[36:37], v[38:39]
	global_store_dwordx4 v[50:51], v[34:37], off offset:528

; __device__ __forceinline__ float bflo(unsigned u) { return __uint_as_float(u << 16); }
; __device__ __forceinline__ float bfhi(unsigned u) { return __uint_as_float(u & 0xffff0000u); }
;     __device__ __forceinline__ void operator()(const f32x4 (&acc)[2][2][4][2], const Unit& u, int wr, int wc, int fr, int fq) const {
;     ...
;             for (int m = 0; m < 4; ++m) { const int r = row0 + ai * HALF + m * 16; float* dst = nullptr;
;                 if (r < MP) { const int b = r / TP, t = r - b * TP; if (t >= NMETA) dst = out + O_YP + ((size_t)b * SEQ + (t - NMETA)) * D; }
;                 else if (r < M) dst = out + O_YS + (size_t)(r - MP) * D;
;                 if (dst) {
; #pragma unroll
;                     for (int bj = 0; bj < 2; ++bj) { const u32x4 q = o[m][bj]; const f32x4 v0 = acc[ai][bj][m][0], v1 = acc[ai][bj][m][1];
;                         *(f32x4*)(dst + col0 + bj * HALF) = (f32x4){bflo(q.x) + v0[0], bfhi(q.x) + v0[1], bflo(q.y) + v0[2], bfhi(q.y) + v0[3]};
;                         *(f32x4*)(dst + col0 + bj * HALF + 4) = (f32x4){bflo(q.z) + v1[0], bfhi(q.z) + v1[1], bflo(q.w) + v1[2], bfhi(q.w) + v1[3]}; } } }
.LBB0_1190:
	v_lshlrev_b32_e32 v36, 16, v78
	v_and_b32_e32 v37, 0xffff0000, v78
	v_pk_add_f32 v[30:31], v[30:31], v[36:37]
	v_lshlrev_b32_e32 v36, 16, v79
	v_and_b32_e32 v37, 0xffff0000, v79
	v_lshl_add_u64 v[34:35], v[174:175], 2, v[34:35]
	v_pk_add_f32 v[32:33], v[32:33], v[36:37]
	global_store_dwordx4 v[34:35], v[30:33], off
	s_nop 1
	v_lshlrev_b32_e32 v30, 16, v80
	v_and_b32_e32 v31, 0xffff0000, v80
	v_pk_add_f32 v[26:27], v[26:27], v[30:31]
	v_lshlrev_b32_e32 v30, 16, v81
	v_and_b32_e32 v31, 0xffff0000, v81
	v_pk_add_f32 v[28:29], v[28:29], v[30:31]
	global_store_dwordx4 v[34:35], v[26:29], off offset:16
	s_nop 1
	v_lshlrev_b32_e32 v26, 16, v74
	v_and_b32_e32 v27, 0xffff0000, v74
	v_pk_add_f32 v[22:23], v[22:23], v[26:27]
	v_lshlrev_b32_e32 v26, 16, v75
	v_and_b32_e32 v27, 0xffff0000, v75
	v_pk_add_f32 v[24:25], v[24:25], v[26:27]
	global_store_dwordx4 v[34:35], v[22:25], off offset:512
	s_nop 1
	v_lshlrev_b32_e32 v22, 16, v76
	v_and_b32_e32 v23, 0xffff0000, v76
	v_pk_add_f32 v[18:19], v[18:19], v[22:23]
	v_lshlrev_b32_e32 v22, 16, v77
	v_and_b32_e32 v23, 0xffff0000, v77
	v_pk_add_f32 v[20:21], v[20:21], v[22:23]
	global_store_dwordx4 v[34:35], v[18:21], off offset:528

; __device__ __forceinline__ float bflo(unsigned u) { return __uint_as_float(u << 16); }
; __device__ __forceinline__ float bfhi(unsigned u) { return __uint_as_float(u & 0xffff0000u); }
;     __device__ __forceinline__ void operator()(const f32x4 (&acc)[2][2][4][2], const Unit& u, int wr, int wc, int fr, int fq) const {
;     ...
;             for (int m = 0; m < 4; ++m) { const int r = row0 + ai * HALF + m * 16; float* dst = nullptr;
;                 if (r < MP) { const int b = r / TP, t = r - b * TP; if (t >= NMETA) dst = out + O_YP + ((size_t)b * SEQ + (t - NMETA)) * D; }
;                 else if (r < M) dst = out + O_YS + (size_t)(r - MP) * D;
;                 if (dst) {
; #pragma unroll
;                     for (int bj = 0; bj < 2; ++bj) { const u32x4 q = o[m][bj]; const f32x4 v0 = acc[ai][bj][m][0], v1 = acc[ai][bj][m][1];
;                         *(f32x4*)(dst + col0 + bj * HALF) = (f32x4){bflo(q.x) + v0[0], bfhi(q.x) + v0[1], bflo(q.y) + v0[2], bfhi(q.y) + v0[3]};
;                         *(f32x4*)(dst + col0 + bj * HALF + 4) = (f32x4){bflo(q.z) + v1[0], bfhi(q.z) + v1[1], bflo(q.w) + v1[2], bfhi(q.w) + v1[3]}; } } }
; template <class Epi, class Sched, bool ALIGN_EPI = false, bool SP2 = false>
; __device__ __forceinline__ void gemm_phase(LAS unsigned char* lds, const Gemm g, const Sched& S, const Epi& E) {
;     ...
;         E(acc, cur, wr, wc, fr, fq); S.done(cur);
;         if (!has_next) break;
.LBB0_1209:
	v_lshlrev_b32_e32 v20, 16, v70
	v_and_b32_e32 v21, 0xffff0000, v70
	v_pk_add_f32 v[14:15], v[14:15], v[20:21]
	v_lshlrev_b32_e32 v20, 16, v71
	v_and_b32_e32 v21, 0xffff0000, v71
	v_lshl_add_u64 v[18:19], v[174:175], 2, v[18:19]
	v_pk_add_f32 v[16:17], v[16:17], v[20:21]
	global_store_dwordx4 v[18:19], v[14:17], off
	s_nop 1
	v_lshlrev_b32_e32 v14, 16, v72
	v_and_b32_e32 v15, 0xffff0000, v72
	v_pk_add_f32 v[10:11], v[10:11], v[14:15]
	v_lshlrev_b32_e32 v14, 16, v73
	v_and_b32_e32 v15, 0xffff0000, v73
	v_pk_add_f32 v[12:13], v[12:13], v[14:15]
	global_store_dwordx4 v[18:19], v[10:13], off offset:16
	s_nop 1
	v_lshlrev_b32_e32 v10, 16, v66
	v_and_b32_e32 v11, 0xffff0000, v66
	v_pk_add_f32 v[6:7], v[6:7], v[10:11]
	v_lshlrev_b32_e32 v10, 16, v67
	v_and_b32_e32 v11, 0xffff0000, v67
	v_pk_add_f32 v[8:9], v[8:9], v[10:11]
	global_store_dwordx4 v[18:19], v[6:9], off offset:512
	s_nop 1
	v_lshlrev_b32_e32 v6, 16, v68
	v_and_b32_e32 v7, 0xffff0000, v68
	v_pk_add_f32 v[2:3], v[2:3], v[6:7]
	v_lshlrev_b32_e32 v6, 16, v69
	v_and_b32_e32 v7, 0xffff0000, v69
	v_pk_add_f32 v[4:5], v[4:5], v[6:7]
	global_store_dwordx4 v[18:19], v[2:5], off offset:528
	s_or_b64 exec, exec, s[42:43]
	s_and_b64 vcc, exec, s[38:39]
	s_mov_b64 s[38:39], -1
	s_cbranch_vccnz .LBB0_1146
